# grid barrier waiters poll the TOP arrival counter (target (gen+1)*nx) instead of TOPGEN
# speedup vs baseline: 1.0019x; 1.0019x over previous
.LBB0_160:
	s_or_b64 exec, exec, s[8:9]
	v_cvt_f32_u32_e32 v5, v3
	s_waitcnt vmcnt(0)
	v_readfirstlane_b32 s6, v4
	v_sub_u32_e32 v4, 0, v3
	v_rcp_iflag_f32_e32 v5, v5
	v_add_u32_e32 v6, s6, v2
	v_mul_f32_e32 v5, 0x4f7ffffe, v5
	v_cvt_u32_f32_e32 v5, v5
	v_mul_lo_u32 v2, v4, v5
	v_mul_hi_u32 v2, v5, v2
	v_add_u32_e32 v2, v5, v2
	v_mul_hi_u32 v2, v6, v2
	v_mul_lo_u32 v4, v2, v3
	v_sub_u32_e32 v4, v6, v4
	v_add_u32_e32 v5, 1, v2
	v_cmp_ge_u32_e32 vcc, v4, v3
	s_nop 1
	v_cndmask_b32_e32 v2, v2, v5, vcc
	v_sub_u32_e32 v5, v4, v3
	v_cndmask_b32_e32 v4, v4, v5, vcc
	v_add_u32_e32 v5, 1, v2
	v_cmp_ge_u32_e32 vcc, v4, v3
	v_add_u32_e32 v4, 1, v6
	s_nop 0
	v_cndmask_b32_e32 v2, v2, v5, vcc
	v_mul_lo_u32 v5, v3, v2
	v_add_u32_e32 v3, v5, v3
	v_cmp_ne_u32_e32 vcc, v4, v3
	s_and_saveexec_b64 s[6:7], vcc
	s_xor_b64 s[6:7], exec, s[6:7]
	s_cbranch_execz .LBB0_174
	s_waitcnt lgkmcnt(0)
	s_add_u32 s12, s94, 0xb3d5800
	s_addc_u32 s13, s95, 0
	v_add_u32_e32 v2, 1, v2
	v_mul_lo_u32 v2, v2, v1
	v_mov_b32_e32 v1, 0
	global_load_dword v1, v1, s[12:13] sc1
	s_waitcnt vmcnt(0)
	v_cmp_lt_u32_e32 vcc, v1, v2
	s_and_saveexec_b64 s[8:9], vcc
	s_cbranch_execz .LBB0_173
	s_add_u32 s10, s94, 0xb3d2600
	s_addc_u32 s11, s95, 0
	s_mov_b32 s24, 1
	s_mov_b64 s[14:15], 0
	v_mov_b32_e32 v1, 0
	s_branch .LBB0_164

.LBB0_168:
	global_load_dword v3, v1, s[12:13] sc1
	s_add_i32 s24, s24, 1
	s_mov_b64 s[20:21], -1
	s_waitcnt vmcnt(0)
	v_cmp_ge_u32_e32 vcc, v3, v2
	s_orn2_b64 s[18:19], vcc, exec
	s_branch .LBB0_163

.LBB0_177:
	s_or_b64 exec, exec, s[8:9]
	v_cvt_f32_u32_e32 v4, v1
	s_waitcnt vmcnt(0)
	v_readfirstlane_b32 s6, v3
	s_add_u32 s8, s94, 0xb3d5900
	s_addc_u32 s9, s95, 0
	v_rcp_iflag_f32_e32 v4, v4
	v_add_u32_e32 v2, s6, v2
	v_add_u32_e32 v5, 1, v2
	s_mov_b64 s[10:11], -1
	v_mul_f32_e32 v3, 0x4f7ffffe, v4
	v_cvt_u32_f32_e32 v3, v3
	v_sub_u32_e32 v4, 0, v1
	v_mul_lo_u32 v4, v4, v3
	v_mul_hi_u32 v4, v3, v4
	v_add_u32_e32 v3, v3, v4
	v_mul_hi_u32 v3, v2, v3
	v_mul_lo_u32 v4, v3, v1
	v_sub_u32_e32 v2, v2, v4
	v_add_u32_e32 v6, 1, v3
	v_cmp_ge_u32_e32 vcc, v2, v1
	v_sub_u32_e32 v4, v2, v1
	s_nop 0
	v_cndmask_b32_e32 v3, v3, v6, vcc
	v_cndmask_b32_e32 v2, v2, v4, vcc
	v_add_u32_e32 v4, 1, v3
	v_cmp_ge_u32_e32 vcc, v2, v1
	s_nop 1
	v_cndmask_b32_e32 v4, v3, v4, vcc
	v_mul_lo_u32 v2, v1, v4
	v_add_u32_e32 v1, v2, v1
	v_cmp_ne_u32_e32 vcc, v5, v1
	v_mov_b32_e32 v4, v1
	v_mov_b64_e32 v[2:3], s[8:9]
	s_and_saveexec_b64 s[6:7], vcc
	s_cbranch_execz .LBB0_189
	s_sub_u32 s8, s8, 0x100
	s_subb_u32 s9, s9, 0
	v_mov_b32_e32 v1, 0
	global_load_dword v2, v1, s[8:9] sc1
	s_mov_b64 s[14:15], 0
	s_waitcnt vmcnt(0)
	v_cmp_lt_u32_e32 vcc, v2, v4
	s_and_saveexec_b64 s[12:13], vcc
	s_cbranch_execz .LBB0_188
	s_add_u32 s10, s94, 0xb3d2600
	s_addc_u32 s11, s95, 0
	s_mov_b32 s24, 1
	s_branch .LBB0_181

.LBB0_185:
	global_load_dword v2, v1, s[8:9] sc1
	s_add_i32 s24, s24, 1
	s_mov_b64 s[18:19], -1
	s_waitcnt vmcnt(0)
	v_cmp_ge_u32_e32 vcc, v2, v4
	s_orn2_b64 s[22:23], vcc, exec
	s_branch .LBB0_180

.LBB0_544:
	s_or_b64 exec, exec, s[8:9]
	v_cvt_f32_u32_e32 v6, v4
	s_waitcnt vmcnt(0)
	v_readfirstlane_b32 s6, v5
	v_sub_u32_e32 v5, 0, v4
	v_rcp_iflag_f32_e32 v6, v6
	v_add_u32_e32 v7, s6, v3
	v_mul_f32_e32 v6, 0x4f7ffffe, v6
	v_cvt_u32_f32_e32 v6, v6
	v_mul_lo_u32 v3, v5, v6
	v_mul_hi_u32 v3, v6, v3
	v_add_u32_e32 v3, v6, v3
	v_mul_hi_u32 v3, v7, v3
	v_mul_lo_u32 v5, v3, v4
	v_sub_u32_e32 v5, v7, v5
	v_add_u32_e32 v6, 1, v3
	v_cmp_ge_u32_e32 vcc, v5, v4
	s_nop 1
	v_cndmask_b32_e32 v3, v3, v6, vcc
	v_sub_u32_e32 v6, v5, v4
	v_cndmask_b32_e32 v5, v5, v6, vcc
	v_add_u32_e32 v6, 1, v3
	v_cmp_ge_u32_e32 vcc, v5, v4
	v_add_u32_e32 v5, 1, v7
	s_nop 0
	v_cndmask_b32_e32 v3, v3, v6, vcc
	v_mul_lo_u32 v6, v4, v3
	v_add_u32_e32 v4, v6, v4
	v_cmp_ne_u32_e32 vcc, v5, v4
	s_and_saveexec_b64 s[6:7], vcc
	s_xor_b64 s[6:7], exec, s[6:7]
	s_cbranch_execz .LBB0_558
	s_waitcnt lgkmcnt(0)
	s_add_u32 s12, s94, 0xb3d5800
	s_addc_u32 s13, s95, 0
	v_add_u32_e32 v3, 1, v3
	v_mul_lo_u32 v3, v3, v2
	v_mov_b32_e32 v2, 0
	global_load_dword v2, v2, s[12:13] sc1
	s_waitcnt vmcnt(0)
	v_cmp_lt_u32_e32 vcc, v2, v3
	s_and_saveexec_b64 s[8:9], vcc
	s_cbranch_execz .LBB0_557
	s_add_u32 s10, s94, 0xb3d2600
	s_addc_u32 s11, s95, 0
	s_mov_b32 s24, 1
	s_mov_b64 s[14:15], 0
	v_mov_b32_e32 v2, 0
	s_branch .LBB0_548

.LBB0_552:
	global_load_dword v4, v2, s[12:13] sc1
	s_add_i32 s24, s24, 1
	s_mov_b64 s[20:21], -1
	s_waitcnt vmcnt(0)
	v_cmp_ge_u32_e32 vcc, v4, v3
	s_orn2_b64 s[18:19], vcc, exec
	s_branch .LBB0_547

.LBB0_561:
	s_or_b64 exec, exec, s[8:9]
	v_cvt_f32_u32_e32 v5, v2
	s_waitcnt vmcnt(0)
	v_readfirstlane_b32 s6, v4
	s_add_u32 s8, s94, 0xb3d5900
	s_addc_u32 s9, s95, 0
	v_rcp_iflag_f32_e32 v5, v5
	v_add_u32_e32 v3, s6, v3
	v_add_u32_e32 v6, 1, v3
	s_mov_b64 s[10:11], -1
	v_mul_f32_e32 v4, 0x4f7ffffe, v5
	v_cvt_u32_f32_e32 v4, v4
	v_sub_u32_e32 v5, 0, v2
	v_mul_lo_u32 v5, v5, v4
	v_mul_hi_u32 v5, v4, v5
	v_add_u32_e32 v4, v4, v5
	v_mul_hi_u32 v4, v3, v4
	v_mul_lo_u32 v5, v4, v2
	v_sub_u32_e32 v3, v3, v5
	v_add_u32_e32 v7, 1, v4
	v_cmp_ge_u32_e32 vcc, v3, v2
	v_sub_u32_e32 v5, v3, v2
	s_nop 0
	v_cndmask_b32_e32 v4, v4, v7, vcc
	v_cndmask_b32_e32 v3, v3, v5, vcc
	v_add_u32_e32 v5, 1, v4
	v_cmp_ge_u32_e32 vcc, v3, v2
	s_nop 1
	v_cndmask_b32_e32 v4, v4, v5, vcc
	v_mul_lo_u32 v3, v2, v4
	v_add_u32_e32 v2, v3, v2
	v_cmp_ne_u32_e32 vcc, v6, v2
	v_mov_b32_e32 v4, v2
	v_mov_b64_e32 v[2:3], s[8:9]
	s_and_saveexec_b64 s[6:7], vcc
	s_cbranch_execz .LBB0_573
	s_sub_u32 s8, s8, 0x100
	s_subb_u32 s9, s9, 0
	v_mov_b32_e32 v2, 0
	global_load_dword v3, v2, s[8:9] sc1
	s_mov_b64 s[14:15], 0
	s_waitcnt vmcnt(0)
	v_cmp_lt_u32_e32 vcc, v3, v4
	s_and_saveexec_b64 s[12:13], vcc
	s_cbranch_execz .LBB0_572
	s_add_u32 s10, s94, 0xb3d2600
	s_addc_u32 s11, s95, 0
	s_mov_b32 s24, 1
	s_branch .LBB0_565

.LBB0_569:
	global_load_dword v3, v2, s[8:9] sc1
	s_add_i32 s24, s24, 1
	s_mov_b64 s[18:19], -1
	s_waitcnt vmcnt(0)
	v_cmp_ge_u32_e32 vcc, v3, v4
	s_orn2_b64 s[22:23], vcc, exec
	s_branch .LBB0_564

.LBB0_1128:
	s_or_b64 exec, exec, s[6:7]
	v_cvt_f32_u32_e32 v5, v3
	s_waitcnt vmcnt(0)
	v_readfirstlane_b32 s4, v4
	v_sub_u32_e32 v4, 0, v3
	v_rcp_iflag_f32_e32 v5, v5
	v_add_u32_e32 v6, s4, v2
	v_mul_f32_e32 v5, 0x4f7ffffe, v5
	v_cvt_u32_f32_e32 v5, v5
	v_mul_lo_u32 v2, v4, v5
	v_mul_hi_u32 v2, v5, v2
	v_add_u32_e32 v2, v5, v2
	v_mul_hi_u32 v2, v6, v2
	v_mul_lo_u32 v4, v2, v3
	v_sub_u32_e32 v4, v6, v4
	v_add_u32_e32 v5, 1, v2
	v_cmp_ge_u32_e32 vcc, v4, v3
	s_nop 1
	v_cndmask_b32_e32 v2, v2, v5, vcc
	v_sub_u32_e32 v5, v4, v3
	v_cndmask_b32_e32 v4, v4, v5, vcc
	v_add_u32_e32 v5, 1, v2
	v_cmp_ge_u32_e32 vcc, v4, v3
	v_add_u32_e32 v4, 1, v6
	s_nop 0
	v_cndmask_b32_e32 v2, v2, v5, vcc
	v_mul_lo_u32 v5, v3, v2
	v_add_u32_e32 v3, v5, v3
	v_cmp_ne_u32_e32 vcc, v4, v3
	s_and_saveexec_b64 s[4:5], vcc
	s_xor_b64 s[4:5], exec, s[4:5]
	s_cbranch_execz .LBB0_1142
	s_waitcnt lgkmcnt(0)
	s_add_u32 s10, s94, 0xb3d5800
	s_addc_u32 s11, s95, 0
	v_add_u32_e32 v2, 1, v2
	v_mul_lo_u32 v2, v2, v1
	v_mov_b32_e32 v1, 0
	global_load_dword v1, v1, s[10:11] sc1
	s_waitcnt vmcnt(0)
	v_cmp_lt_u32_e32 vcc, v1, v2
	s_and_saveexec_b64 s[6:7], vcc
	s_cbranch_execz .LBB0_1141
	s_add_u32 s8, s94, 0xb3d2600
	s_addc_u32 s9, s95, 0
	s_mov_b32 s22, 1
	s_mov_b64 s[12:13], 0
	v_mov_b32_e32 v1, 0
	s_branch .LBB0_1132

.LBB0_1136:
	global_load_dword v3, v1, s[10:11] sc1
	s_add_i32 s22, s22, 1
	s_mov_b64 s[18:19], -1
	s_waitcnt vmcnt(0)
	v_cmp_ge_u32_e32 vcc, v3, v2
	s_orn2_b64 s[16:17], vcc, exec
	s_branch .LBB0_1131

.LBB0_1145:
	s_or_b64 exec, exec, s[6:7]
	v_cvt_f32_u32_e32 v4, v1
	s_waitcnt vmcnt(0)
	v_readfirstlane_b32 s4, v3
	s_add_u32 s6, s94, 0xb3d5900
	s_addc_u32 s7, s95, 0
	v_rcp_iflag_f32_e32 v4, v4
	v_add_u32_e32 v2, s4, v2
	v_add_u32_e32 v5, 1, v2
	s_mov_b64 s[8:9], -1
	v_mul_f32_e32 v3, 0x4f7ffffe, v4
	v_cvt_u32_f32_e32 v3, v3
	v_sub_u32_e32 v4, 0, v1
	v_mul_lo_u32 v4, v4, v3
	v_mul_hi_u32 v4, v3, v4
	v_add_u32_e32 v3, v3, v4
	v_mul_hi_u32 v3, v2, v3
	v_mul_lo_u32 v4, v3, v1
	v_sub_u32_e32 v2, v2, v4
	v_add_u32_e32 v6, 1, v3
	v_cmp_ge_u32_e32 vcc, v2, v1
	v_sub_u32_e32 v4, v2, v1
	s_nop 0
	v_cndmask_b32_e32 v3, v3, v6, vcc
	v_cndmask_b32_e32 v2, v2, v4, vcc
	v_add_u32_e32 v4, 1, v3
	v_cmp_ge_u32_e32 vcc, v2, v1
	s_nop 1
	v_cndmask_b32_e32 v4, v3, v4, vcc
	v_mul_lo_u32 v2, v1, v4
	v_add_u32_e32 v1, v2, v1
	v_cmp_ne_u32_e32 vcc, v5, v1
	v_mov_b32_e32 v4, v1
	v_mov_b64_e32 v[2:3], s[6:7]
	s_and_saveexec_b64 s[4:5], vcc
	s_cbranch_execz .LBB0_1157
	s_sub_u32 s6, s6, 0x100
	s_subb_u32 s7, s7, 0
	v_mov_b32_e32 v1, 0
	global_load_dword v2, v1, s[6:7] sc1
	s_mov_b64 s[12:13], 0
	s_waitcnt vmcnt(0)
	v_cmp_lt_u32_e32 vcc, v2, v4
	s_and_saveexec_b64 s[10:11], vcc
	s_cbranch_execz .LBB0_1156
	s_add_u32 s8, s94, 0xb3d2600
	s_addc_u32 s9, s95, 0
	s_mov_b32 s22, 1
	s_branch .LBB0_1149

.LBB0_1153:
	global_load_dword v2, v1, s[6:7] sc1
	s_add_i32 s22, s22, 1
	s_mov_b64 s[16:17], -1
	s_waitcnt vmcnt(0)
	v_cmp_ge_u32_e32 vcc, v2, v4
	s_orn2_b64 s[20:21], vcc, exec
	s_branch .LBB0_1148
